# phase 0 reduced to exactly 6 static rounds: w_out + 96 w_up transposes to the phase-2 queue tail, 336 w_down transposes to the phase-7 workgroups that own 11 instead of 12 tiles
# speedup vs baseline: 1.0137x; 1.0137x over previous
.LBB0_33:
	s_or_b64 exec, exec, s[4:5]
	v_writelane_b32 v252, s60, 8
	s_cmpk_gt_i32 s2, 0xe2f
	v_and_b32_e32 v161, 63, v162
	v_writelane_b32 v252, s61, 9
	v_writelane_b32 v252, s62, 10
	v_writelane_b32 v252, s63, 11
	v_writelane_b32 v252, s64, 12
	v_writelane_b32 v252, s65, 13
	v_writelane_b32 v252, s66, 14
	v_writelane_b32 v252, s67, 15
	v_writelane_b32 v252, s68, 16
	v_writelane_b32 v252, s69, 17
	v_writelane_b32 v252, s70, 18
	v_writelane_b32 v252, s71, 19
	v_writelane_b32 v252, s72, 20
	v_writelane_b32 v252, s73, 21
	v_lshrrev_b32_e32 v160, 6, v162
	v_lshrrev_b32_e32 v228, 5, v162
	v_lshlrev_b32_e32 v229, 2, v162
	v_mbcnt_lo_u32_b32 v230, -1, 0
	v_writelane_b32 v252, s74, 22
	v_writelane_b32 v252, s75, 23
	s_cbranch_scc1 .LBB0_59
	s_load_dword s11, s[0:1], 0x1b8
	s_waitcnt lgkmcnt(0)
	s_load_dwordx16 s[12:27], s[0:1], 0xc0
	v_lshlrev_b32_e32 v1, 2, v162
	v_mov_b32_e32 v167, 0
	v_and_b32_e32 v166, 0x7c, v1
	s_movk_i32 s4, 0x84
	s_waitcnt lgkmcnt(0)
	v_lshl_add_u64 v[170:171], s[16:17], 0, v[166:167]
	s_load_dwordx8 s[16:23], s[0:1], 0x180
	v_lshl_add_u64 v[174:175], s[12:13], 0, v[166:167]
	v_lshlrev_b32_e32 v0, 2, v161
	v_lshlrev_b32_e32 v168, 4, v161
	v_mul_u32_u24_e32 v1, 0x74, v161
	s_waitcnt lgkmcnt(0)
	s_mov_b64 s[58:59], s[22:23]
	s_mov_b64 s[56:57], s[20:21]
	s_mov_b64 s[54:55], s[18:19]
	s_mov_b64 s[52:53], s[16:17]
	s_load_dwordx16 s[12:27], s[0:1], 0x80
	v_lshlrev_b32_e32 v2, 2, v160
	v_mad_u32_u24 v231, v228, s4, v166
	s_lshl_b32 s4, s2, 3
	v_mbcnt_hi_u32_b32 v232, -1, v230
	s_waitcnt lgkmcnt(0)
	v_lshl_add_u64 v[178:179], s[24:25], 0, v[166:167]
	v_lshl_add_u64 v[182:183], s[14:15], 0, v[166:167]
	s_load_dwordx16 s[12:27], s[0:1], 0x140
	v_add3_u32 v163, v168, v1, v2
	v_lshlrev_b32_e32 v2, 1, v161
	v_mov_b32_e32 v3, v167
	v_lshl_add_u64 v[186:187], s[36:37], 0, v[166:167]
	v_mov_b32_e32 v169, v167
	v_lshlrev_b32_e32 v166, 3, v161
	s_waitcnt lgkmcnt(0)
	s_add_i32 s12, s4, 0x7ffff000
	s_lshl_b32 s4, s2, 4
	v_lshlrev_b32_e32 v194, 2, v0
	v_and_b32_e32 v0, 64, v232
	v_lshl_add_u64 v[172:173], s[56:57], 0, v[2:3]
	v_lshl_add_u64 v[176:177], s[54:55], 0, v[2:3]
	v_lshl_add_u64 v[180:181], s[52:53], 0, v[2:3]
	v_lshl_add_u64 v[184:185], s[26:27], 0, v[2:3]
	v_lshl_add_u64 v[188:189], s[24:25], 0, v[2:3]
	v_lshl_add_u64 v[190:191], s[74:75], 0, v[168:169]
	v_readfirstlane_b32 s98, v160
	s_nop 3
	s_lshl_b32 s98, s98, 12
	s_add_u32 s98, s98, 0xb000
	s_mov_b32 m0, s98
	v_lshl_add_u32 v250, v161, 4, s98
	global_load_lds_dwordx4 v[190:191], off
	global_load_lds_dwordx4 v[190:191], off offset:1024
	global_load_lds_dwordx4 v[190:191], off offset:2048
	global_load_lds_dwordx4 v[190:191], off offset:3072
	v_lshl_add_u64 v[192:193], s[58:59], 0, v[166:167]
	s_add_i32 s13, s4, 0x7fffec00
	v_mov_b32_e32 v169, 0x358637bd
	v_add_u32_e32 v233, 64, v0
	v_xor_b32_e32 v234, 32, v232
	v_xor_b32_e32 v235, 16, v232
	v_xor_b32_e32 v236, 8, v232
	v_xor_b32_e32 v237, 4, v232
	v_xor_b32_e32 v238, 2, v232
	v_xor_b32_e32 v239, 1, v232
	s_lshl_b32 s14, s11, 3
	s_lshl_b32 s15, s11, 8
	s_lshl_b32 s16, s11, 4
	s_movk_i32 s17, 0x4000
	s_mov_b32 s18, 0x800000
	s_mov_b32 s19, 0x10000
	s_mov_b32 s20, 0x28000
	s_mov_b32 s21, 0x50000
	s_mov_b32 s22, 0x58000
	s_mov_b32 s23, 0x78000
	s_mov_b32 s24, 0xa0000
	s_mov_b32 s25, 0xb0000
	s_mov_b32 s26, 0xc8000
	s_mov_b32 s27, 0xf0000
	s_mov_b32 s33, s2
	s_mov_b32 s7, 0
	v_cmp_eq_u32_e64 s[4:5], 0, v161
	s_mov_b32 s32, 0
	s_cmpk_lt_u32 s33, 0x180
	s_cbranch_scc1 .Lp0_noshift
	s_addk_i32 s33, 0xe0
	s_add_i32 s12, s12, 0x700
	s_add_i32 s10, s10, 0xe000
	s_add_i32 s13, s13, 0xe00
	s_mov_b32 s32, 1

.LBB0_35:
	s_add_i32 s33, s33, s11
	s_add_i32 s12, s12, s14
	s_add_i32 s10, s10, s15
	s_add_i32 s13, s13, s16
	s_cmp_eq_u32 s32, 0
	s_cbranch_scc0 .Lp0_s1
	s_addk_i32 s33, 0xe0
	s_add_i32 s12, s12, 0x700
	s_add_i32 s10, s10, 0xe000
	s_add_i32 s13, s13, 0xe00
	s_mov_b32 s32, 1
	s_branch .Lp0_s2
.Lp0_s1:
	s_cmp_eq_u32 s32, 1
	s_cbranch_scc0 .Lp0_s2
	s_cmpk_lt_i32 s33, 0x4c0
	s_cbranch_scc1 .Lp0_s2
	s_addk_i32 s33, 0x150
	s_add_i32 s12, s12, 0xa80
	s_add_i32 s10, s10, 0x15000
	s_add_i32 s13, s13, 0x1500
	s_mov_b32 s32, 2

.LBB0_196:
	s_or_b64 exec, exec, s[0:1]
	s_waitcnt lgkmcnt(0)
	s_barrier
	ds_read_b32 v0, v194
	s_movk_i32 s0, 0x65f
	s_waitcnt lgkmcnt(0)
	v_cmp_lt_i32_e32 vcc, s0, v0
	v_readfirstlane_b32 s36, v0
	s_mov_b64 s[0:1], -1
	s_cbranch_vccnz .LBB0_191
	s_cmpk_gt_i32 s36, 0xff
	s_cbranch_scc0 .LBB0_316
	s_cmpk_gt_u32 s36, 0x4ff
	s_cbranch_scc0 .LBB0_212
	s_cmpk_gt_u32 s36, 0x57f
	s_cbranch_scc1 .Lp2_tr
	v_readlane_b32 s12, v252, 30
	v_readlane_b32 s13, v252, 31
	s_barrier
	s_and_saveexec_b64 s[0:1], s[12:13]
	v_readlane_b32 s68, v251, 8
	v_readlane_b32 s78, v251, 18
	v_readlane_b32 s79, v251, 19
	v_readlane_b32 s69, v251, 9
	v_readlane_b32 s70, v251, 10
	v_readlane_b32 s71, v251, 11
	v_readlane_b32 s72, v251, 12
	v_readlane_b32 s73, v251, 13
	v_readlane_b32 s74, v251, 14
	v_readlane_b32 s75, v251, 15
	v_readlane_b32 s76, v251, 16
	v_readlane_b32 s77, v251, 17
	v_readlane_b32 s80, v251, 20
	v_readlane_b32 s81, v251, 21
	v_readlane_b32 s82, v251, 22
	v_readlane_b32 s83, v251, 23
	s_cbranch_execz .LBB0_202
	s_mov_b64 s[14:15], 0
	v_mov_b32_e32 v2, v229
	v_mov_b32_e32 v3, v103

.LBB0_796:
	s_or_b64 exec, exec, s[0:1]
	s_cmp_lt_u32 s84, 50
	s_cbranch_scc1 .Lp7_tr_done
	s_mul_i32 s31, s62, 14
	s_add_u32 s31, s31, s84
	s_sub_u32 s31, s31, 50
	s_mov_b32 s30, 0
	s_mov_b32 s16, 0x1000
	s_mov_b32 s17, 0x1600
	s_lshl_b32 s24, s16, 3
	s_lshl_b32 s25, s17, 2
	v_and_b32_e32 v58, 31, v162
	v_lshrrev_b32_e32 v59, 5, v162
	v_lshlrev_b32_e32 v60, 2, v58
	v_mad_u32_u24 v60, v59, s16, v60
	v_mul_u32_u24_e32 v61, 33, v59
	v_add_lshl_u32 v61, v61, v58, 2
	v_and_b32_e32 v62, 63, v162
	v_lshrrev_b32_e32 v63, 6, v162
	v_mul_u32_u24_e32 v64, 33, v62
	v_add_lshl_u32 v64, v64, v63, 2
	v_lshlrev_b32_e32 v65, 1, v62
	v_mad_u32_u24 v65, v63, s17, v65
.Lp7_tr_loop:
	s_mul_hi_u32 s5, s31, 0x1745d175
	s_mul_i32 s6, s5, 11
	s_sub_u32 s6, s31, s6
	s_lshl_b32 s5, s5, 5
	s_lshl_b32 s6, s6, 8
	v_readlane_b32 s20, v251, 44
	v_readlane_b32 s21, v251, 45
	v_readlane_b32 s22, v251, 4
	v_readlane_b32 s23, v251, 5
	s_mul_i32 s7, s6, s16
	s_lshl_b32 s8, s5, 2
	s_add_u32 s7, s7, s8
	s_add_u32 s20, s20, s7
	s_addc_u32 s21, s21, 0
	s_mul_i32 s7, s5, s17
	s_lshl_b32 s8, s6, 1
	s_add_u32 s7, s7, s8
	s_add_u32 s22, s22, s7
	s_addc_u32 s23, s23, 0
	s_waitcnt lgkmcnt(0)
	s_barrier
	s_mov_b64 s[26:27], s[20:21]
	global_load_dword v18, v60, s[26:27]
	s_add_u32 s26, s26, s24
	s_addc_u32 s27, s27, 0
	global_load_dword v19, v60, s[26:27]
	s_add_u32 s26, s26, s24
	s_addc_u32 s27, s27, 0
	global_load_dword v20, v60, s[26:27]
	s_add_u32 s26, s26, s24
	s_addc_u32 s27, s27, 0
	global_load_dword v21, v60, s[26:27]
	s_add_u32 s26, s26, s24
	s_addc_u32 s27, s27, 0
	global_load_dword v22, v60, s[26:27]
	s_add_u32 s26, s26, s24
	s_addc_u32 s27, s27, 0
	global_load_dword v23, v60, s[26:27]
	s_add_u32 s26, s26, s24
	s_addc_u32 s27, s27, 0
	global_load_dword v24, v60, s[26:27]
	s_add_u32 s26, s26, s24
	s_addc_u32 s27, s27, 0
	global_load_dword v25, v60, s[26:27]
	s_add_u32 s26, s26, s24
	s_addc_u32 s27, s27, 0
	global_load_dword v26, v60, s[26:27]
	s_add_u32 s26, s26, s24
	s_addc_u32 s27, s27, 0
	global_load_dword v27, v60, s[26:27]
	s_add_u32 s26, s26, s24
	s_addc_u32 s27, s27, 0
	global_load_dword v28, v60, s[26:27]
	s_add_u32 s26, s26, s24
	s_addc_u32 s27, s27, 0
	global_load_dword v29, v60, s[26:27]
	s_add_u32 s26, s26, s24
	s_addc_u32 s27, s27, 0
	global_load_dword v30, v60, s[26:27]
	s_add_u32 s26, s26, s24
	s_addc_u32 s27, s27, 0
	global_load_dword v31, v60, s[26:27]
	s_add_u32 s26, s26, s24
	s_addc_u32 s27, s27, 0
	global_load_dword v32, v60, s[26:27]
	s_add_u32 s26, s26, s24
	s_addc_u32 s27, s27, 0
	global_load_dword v33, v60, s[26:27]
	s_add_u32 s26, s26, s24
	s_addc_u32 s27, s27, 0
	global_load_dword v34, v60, s[26:27]
	s_add_u32 s26, s26, s24
	s_addc_u32 s27, s27, 0
	global_load_dword v35, v60, s[26:27]
	s_add_u32 s26, s26, s24
	s_addc_u32 s27, s27, 0
	global_load_dword v36, v60, s[26:27]
	s_add_u32 s26, s26, s24
	s_addc_u32 s27, s27, 0
	global_load_dword v37, v60, s[26:27]
	s_add_u32 s26, s26, s24
	s_addc_u32 s27, s27, 0
	global_load_dword v38, v60, s[26:27]
	s_add_u32 s26, s26, s24
	s_addc_u32 s27, s27, 0
	global_load_dword v39, v60, s[26:27]
	s_add_u32 s26, s26, s24
	s_addc_u32 s27, s27, 0
	global_load_dword v40, v60, s[26:27]
	s_add_u32 s26, s26, s24
	s_addc_u32 s27, s27, 0
	global_load_dword v41, v60, s[26:27]
	s_add_u32 s26, s26, s24
	s_addc_u32 s27, s27, 0
	global_load_dword v42, v60, s[26:27]
	s_add_u32 s26, s26, s24
	s_addc_u32 s27, s27, 0
	global_load_dword v43, v60, s[26:27]
	s_add_u32 s26, s26, s24
	s_addc_u32 s27, s27, 0
	global_load_dword v44, v60, s[26:27]
	s_add_u32 s26, s26, s24
	s_addc_u32 s27, s27, 0
	global_load_dword v45, v60, s[26:27]
	s_add_u32 s26, s26, s24
	s_addc_u32 s27, s27, 0
	global_load_dword v46, v60, s[26:27]
	s_add_u32 s26, s26, s24
	s_addc_u32 s27, s27, 0
	global_load_dword v47, v60, s[26:27]
	s_add_u32 s26, s26, s24
	s_addc_u32 s27, s27, 0
	global_load_dword v48, v60, s[26:27]
	s_add_u32 s26, s26, s24
	s_addc_u32 s27, s27, 0
	global_load_dword v49, v60, s[26:27]
	s_waitcnt vmcnt(31)
	ds_write_b32 v61, v18 offset:0
	s_waitcnt vmcnt(30)
	ds_write_b32 v61, v19 offset:1056
	s_waitcnt vmcnt(29)
	ds_write_b32 v61, v20 offset:2112
	s_waitcnt vmcnt(28)
	ds_write_b32 v61, v21 offset:3168
	s_waitcnt vmcnt(27)
	ds_write_b32 v61, v22 offset:4224
	s_waitcnt vmcnt(26)
	ds_write_b32 v61, v23 offset:5280
	s_waitcnt vmcnt(25)
	ds_write_b32 v61, v24 offset:6336
	s_waitcnt vmcnt(24)
	ds_write_b32 v61, v25 offset:7392
	s_waitcnt lgkmcnt(0)
	s_barrier
	ds_read_b32 v50, v64 offset:0
	ds_read_b32 v51, v64 offset:16
	ds_read_b32 v52, v64 offset:32
	ds_read_b32 v53, v64 offset:48
	ds_read_b32 v54, v64 offset:64
	ds_read_b32 v55, v64 offset:80
	ds_read_b32 v56, v64 offset:96
	ds_read_b32 v57, v64 offset:112
	s_mov_b64 s[28:29], s[22:23]
	s_waitcnt lgkmcnt(7)
	v_cvt_pk_bf16_f32 v50, v50, v50
	global_store_short v65, v50, s[28:29] offset:0
	s_add_u32 s28, s28, s25
	s_addc_u32 s29, s29, 0
	s_waitcnt lgkmcnt(6)
	v_cvt_pk_bf16_f32 v51, v51, v51
	global_store_short v65, v51, s[28:29] offset:0
	s_add_u32 s28, s28, s25
	s_addc_u32 s29, s29, 0
	s_waitcnt lgkmcnt(5)
	v_cvt_pk_bf16_f32 v52, v52, v52
	global_store_short v65, v52, s[28:29] offset:0
	s_add_u32 s28, s28, s25
	s_addc_u32 s29, s29, 0
	s_waitcnt lgkmcnt(4)
	v_cvt_pk_bf16_f32 v53, v53, v53
	global_store_short v65, v53, s[28:29] offset:0
	s_add_u32 s28, s28, s25
	s_addc_u32 s29, s29, 0
	s_waitcnt lgkmcnt(3)
	v_cvt_pk_bf16_f32 v54, v54, v54
	global_store_short v65, v54, s[28:29] offset:0
	s_add_u32 s28, s28, s25
	s_addc_u32 s29, s29, 0
	s_waitcnt lgkmcnt(2)
	v_cvt_pk_bf16_f32 v55, v55, v55
	global_store_short v65, v55, s[28:29] offset:0
	s_add_u32 s28, s28, s25
	s_addc_u32 s29, s29, 0
	s_waitcnt lgkmcnt(1)
	v_cvt_pk_bf16_f32 v56, v56, v56
	global_store_short v65, v56, s[28:29] offset:0
	s_add_u32 s28, s28, s25
	s_addc_u32 s29, s29, 0
	s_waitcnt lgkmcnt(0)
	v_cvt_pk_bf16_f32 v57, v57, v57
	global_store_short v65, v57, s[28:29] offset:0
	s_barrier
	s_waitcnt vmcnt(31)
	ds_write_b32 v61, v26 offset:0
	s_waitcnt vmcnt(30)
	ds_write_b32 v61, v27 offset:1056
	s_waitcnt vmcnt(29)
	ds_write_b32 v61, v28 offset:2112
	s_waitcnt vmcnt(28)
	ds_write_b32 v61, v29 offset:3168
	s_waitcnt vmcnt(27)
	ds_write_b32 v61, v30 offset:4224
	s_waitcnt vmcnt(26)
	ds_write_b32 v61, v31 offset:5280
	s_waitcnt vmcnt(25)
	ds_write_b32 v61, v32 offset:6336
	s_waitcnt vmcnt(24)
	ds_write_b32 v61, v33 offset:7392
	s_waitcnt lgkmcnt(0)
	s_barrier
	ds_read_b32 v50, v64 offset:0
	ds_read_b32 v51, v64 offset:16
	ds_read_b32 v52, v64 offset:32
	ds_read_b32 v53, v64 offset:48
	ds_read_b32 v54, v64 offset:64
	ds_read_b32 v55, v64 offset:80
	ds_read_b32 v56, v64 offset:96
	ds_read_b32 v57, v64 offset:112
	s_mov_b64 s[28:29], s[22:23]
	s_waitcnt lgkmcnt(7)
	v_cvt_pk_bf16_f32 v50, v50, v50
	global_store_short v65, v50, s[28:29] offset:128
	s_add_u32 s28, s28, s25
	s_addc_u32 s29, s29, 0
	s_waitcnt lgkmcnt(6)
	v_cvt_pk_bf16_f32 v51, v51, v51
	global_store_short v65, v51, s[28:29] offset:128
	s_add_u32 s28, s28, s25
	s_addc_u32 s29, s29, 0
	s_waitcnt lgkmcnt(5)
	v_cvt_pk_bf16_f32 v52, v52, v52
	global_store_short v65, v52, s[28:29] offset:128
	s_add_u32 s28, s28, s25
	s_addc_u32 s29, s29, 0
	s_waitcnt lgkmcnt(4)
	v_cvt_pk_bf16_f32 v53, v53, v53
	global_store_short v65, v53, s[28:29] offset:128
	s_add_u32 s28, s28, s25
	s_addc_u32 s29, s29, 0
	s_waitcnt lgkmcnt(3)
	v_cvt_pk_bf16_f32 v54, v54, v54
	global_store_short v65, v54, s[28:29] offset:128
	s_add_u32 s28, s28, s25
	s_addc_u32 s29, s29, 0
	s_waitcnt lgkmcnt(2)
	v_cvt_pk_bf16_f32 v55, v55, v55
	global_store_short v65, v55, s[28:29] offset:128
	s_add_u32 s28, s28, s25
	s_addc_u32 s29, s29, 0
	s_waitcnt lgkmcnt(1)
	v_cvt_pk_bf16_f32 v56, v56, v56
	global_store_short v65, v56, s[28:29] offset:128
	s_add_u32 s28, s28, s25
	s_addc_u32 s29, s29, 0
	s_waitcnt lgkmcnt(0)
	v_cvt_pk_bf16_f32 v57, v57, v57
	global_store_short v65, v57, s[28:29] offset:128
	s_barrier
	s_waitcnt vmcnt(31)
	ds_write_b32 v61, v34 offset:0
	s_waitcnt vmcnt(30)
	ds_write_b32 v61, v35 offset:1056
	s_waitcnt vmcnt(29)
	ds_write_b32 v61, v36 offset:2112
	s_waitcnt vmcnt(28)
	ds_write_b32 v61, v37 offset:3168
	s_waitcnt vmcnt(27)
	ds_write_b32 v61, v38 offset:4224
	s_waitcnt vmcnt(26)
	ds_write_b32 v61, v39 offset:5280
	s_waitcnt vmcnt(25)
	ds_write_b32 v61, v40 offset:6336
	s_waitcnt vmcnt(24)
	ds_write_b32 v61, v41 offset:7392
	s_waitcnt lgkmcnt(0)
	s_barrier
	ds_read_b32 v50, v64 offset:0
	ds_read_b32 v51, v64 offset:16
	ds_read_b32 v52, v64 offset:32
	ds_read_b32 v53, v64 offset:48
	ds_read_b32 v54, v64 offset:64
	ds_read_b32 v55, v64 offset:80
	ds_read_b32 v56, v64 offset:96
	ds_read_b32 v57, v64 offset:112
	s_mov_b64 s[28:29], s[22:23]
	s_waitcnt lgkmcnt(7)
	v_cvt_pk_bf16_f32 v50, v50, v50
	global_store_short v65, v50, s[28:29] offset:256
	s_add_u32 s28, s28, s25
	s_addc_u32 s29, s29, 0
	s_waitcnt lgkmcnt(6)
	v_cvt_pk_bf16_f32 v51, v51, v51
	global_store_short v65, v51, s[28:29] offset:256
	s_add_u32 s28, s28, s25
	s_addc_u32 s29, s29, 0
	s_waitcnt lgkmcnt(5)
	v_cvt_pk_bf16_f32 v52, v52, v52
	global_store_short v65, v52, s[28:29] offset:256
	s_add_u32 s28, s28, s25
	s_addc_u32 s29, s29, 0
	s_waitcnt lgkmcnt(4)
	v_cvt_pk_bf16_f32 v53, v53, v53
	global_store_short v65, v53, s[28:29] offset:256
	s_add_u32 s28, s28, s25
	s_addc_u32 s29, s29, 0
	s_waitcnt lgkmcnt(3)
	v_cvt_pk_bf16_f32 v54, v54, v54
	global_store_short v65, v54, s[28:29] offset:256
	s_add_u32 s28, s28, s25
	s_addc_u32 s29, s29, 0
	s_waitcnt lgkmcnt(2)
	v_cvt_pk_bf16_f32 v55, v55, v55
	global_store_short v65, v55, s[28:29] offset:256
	s_add_u32 s28, s28, s25
	s_addc_u32 s29, s29, 0
	s_waitcnt lgkmcnt(1)
	v_cvt_pk_bf16_f32 v56, v56, v56
	global_store_short v65, v56, s[28:29] offset:256
	s_add_u32 s28, s28, s25
	s_addc_u32 s29, s29, 0
	s_waitcnt lgkmcnt(0)
	v_cvt_pk_bf16_f32 v57, v57, v57
	global_store_short v65, v57, s[28:29] offset:256
	s_barrier
	s_waitcnt vmcnt(31)
	ds_write_b32 v61, v42 offset:0
	s_waitcnt vmcnt(30)
	ds_write_b32 v61, v43 offset:1056
	s_waitcnt vmcnt(29)
	ds_write_b32 v61, v44 offset:2112
	s_waitcnt vmcnt(28)
	ds_write_b32 v61, v45 offset:3168
	s_waitcnt vmcnt(27)
	ds_write_b32 v61, v46 offset:4224
	s_waitcnt vmcnt(26)
	ds_write_b32 v61, v47 offset:5280
	s_waitcnt vmcnt(25)
	ds_write_b32 v61, v48 offset:6336
	s_waitcnt vmcnt(24)
	ds_write_b32 v61, v49 offset:7392
	s_waitcnt lgkmcnt(0)
	s_barrier
	ds_read_b32 v50, v64 offset:0
	ds_read_b32 v51, v64 offset:16
	ds_read_b32 v52, v64 offset:32
	ds_read_b32 v53, v64 offset:48
	ds_read_b32 v54, v64 offset:64
	ds_read_b32 v55, v64 offset:80
	ds_read_b32 v56, v64 offset:96
	ds_read_b32 v57, v64 offset:112
	s_mov_b64 s[28:29], s[22:23]
	s_waitcnt lgkmcnt(7)
	v_cvt_pk_bf16_f32 v50, v50, v50
	global_store_short v65, v50, s[28:29] offset:384
	s_add_u32 s28, s28, s25
	s_addc_u32 s29, s29, 0
	s_waitcnt lgkmcnt(6)
	v_cvt_pk_bf16_f32 v51, v51, v51
	global_store_short v65, v51, s[28:29] offset:384
	s_add_u32 s28, s28, s25
	s_addc_u32 s29, s29, 0
	s_waitcnt lgkmcnt(5)
	v_cvt_pk_bf16_f32 v52, v52, v52
	global_store_short v65, v52, s[28:29] offset:384
	s_add_u32 s28, s28, s25
	s_addc_u32 s29, s29, 0
	s_waitcnt lgkmcnt(4)
	v_cvt_pk_bf16_f32 v53, v53, v53
	global_store_short v65, v53, s[28:29] offset:384
	s_add_u32 s28, s28, s25
	s_addc_u32 s29, s29, 0
	s_waitcnt lgkmcnt(3)
	v_cvt_pk_bf16_f32 v54, v54, v54
	global_store_short v65, v54, s[28:29] offset:384
	s_add_u32 s28, s28, s25
	s_addc_u32 s29, s29, 0
	s_waitcnt lgkmcnt(2)
	v_cvt_pk_bf16_f32 v55, v55, v55
	global_store_short v65, v55, s[28:29] offset:384
	s_add_u32 s28, s28, s25
	s_addc_u32 s29, s29, 0
	s_waitcnt lgkmcnt(1)
	v_cvt_pk_bf16_f32 v56, v56, v56
	global_store_short v65, v56, s[28:29] offset:384
	s_add_u32 s28, s28, s25
	s_addc_u32 s29, s29, 0
	s_waitcnt lgkmcnt(0)
	v_cvt_pk_bf16_f32 v57, v57, v57
	global_store_short v65, v57, s[28:29] offset:384
	s_barrier
	s_add_u32 s31, s31, 0x70
	s_add_u32 s30, s30, 1
	s_cmp_lt_u32 s30, 3
	s_cbranch_scc1 .Lp7_tr_loop
.Lp7_tr_done:
	v_readlane_b32 s4, v252, 8
	s_mul_i32 s0, s62, 0x178c
	v_readlane_b32 s12, v252, 16
	v_readlane_b32 s13, v252, 17
	v_readlane_b32 s16, v252, 20
	v_readlane_b32 s17, v252, 21
	s_lshr_b32 s45, s0, 3
	v_readlane_b32 s5, v252, 9
	v_readlane_b32 s6, v252, 10
	v_readlane_b32 s7, v252, 11
	v_readlane_b32 s8, v252, 12
	v_readlane_b32 s9, v252, 13
	v_readlane_b32 s10, v252, 14
	v_readlane_b32 s11, v252, 15
	v_readlane_b32 s14, v252, 18
	v_readlane_b32 s15, v252, 19
	v_readlane_b32 s18, v252, 22
	v_readlane_b32 s19, v252, 23
	s_mov_b64 s[12:13], s[16:17]
	s_mov_b64 s[94:95], s[84:85]
	s_add_i32 s45, s45, s84
	v_readlane_b32 s72, v251, 40
	s_waitcnt lgkmcnt(0)
	v_mov_b32_e32 v0, s12
	v_mov_b32_e32 v1, s13
	v_readlane_b32 s4, v251, 56
	s_addk_i32 s0, 0x178c
	v_readlane_b32 s74, v251, 42
	v_readlane_b32 s75, v251, 43
	v_readlane_b32 s82, v251, 50
	v_readlane_b32 s83, v251, 51
	v_readlane_b32 s18, v252, 6
	s_lshr_b32 s44, s0, 3
	v_bfe_u32 v5, v162, 4, 1
	s_mov_b64 s[82:83], s[74:75]
	v_readlane_b32 s19, v252, 7
	v_and_b32_e32 v6, 30, v99
	v_lshlrev_b32_e32 v4, 8, v5
	s_add_u32 s18, s82, 0x5800
	v_readlane_b32 s5, v251, 57
	v_readlane_b32 s6, v251, 58
	v_readlane_b32 s7, v251, 59
	v_readlane_b32 s8, v251, 60
	v_readlane_b32 s9, v251, 61
	v_readlane_b32 s10, v251, 62
	v_readlane_b32 s11, v251, 63
	v_and_b32_e32 v105, 0x1f0, v100
	v_lshl_or_b32 v7, v6, 2, v4
	s_movk_i32 s4, 0x210
	s_addc_u32 s19, s83, 0
	v_mov_b32_e32 v116, 0
	v_mad_u32_u24 v7, v105, s4, v7
	v_readlane_b32 s4, v251, 0
	s_add_u32 s22, s82, 0xb000
	v_mov_b32_e32 v107, v116
	v_readlane_b32 s5, v251, 1
	v_readlane_b32 s6, v251, 2
	v_readlane_b32 s7, v251, 3
	s_addc_u32 s23, s83, 0
	s_movk_i32 s4, 0x2100
	v_lshl_add_u64 v[100:101], s[6:7], 0, v[106:107]
	s_add_u32 s26, s82, 0x2c00
	v_lshl_or_b32 v107, v5, 5, v6
	v_mad_u64_u32 v[4:5], s[4:5], v228, s4, v[4:5]
	v_add_u32_e32 v111, 0xfffffbe0, v7
	v_add_u32_e32 v113, 0xfffffdf0, v7
	s_addc_u32 s27, s83, 0
	v_lshlrev_b32_e32 v6, 4, v219
	v_mov_b32_e32 v7, v116
	v_lshl_or_b32 v134, v98, 3, v4
	v_lshlrev_b32_e32 v4, 4, v228
	v_lshl_add_u32 v8, v102, 2, v16
	s_add_u32 s28, s82, 0x8400
	v_lshl_add_u64 v[102:103], s[6:7], 0, v[6:7]
	v_sub_u32_e32 v135, 0, v4
	v_lshrrev_b32_e32 v6, 5, v162
	s_mov_b32 s4, 0x16000
	v_mov_b64_e32 v[4:5], s[60:61]
	v_readlane_b32 s16, v252, 4
	v_readlane_b32 s17, v252, 5
	s_addc_u32 s29, s83, 0
	v_mad_u64_u32 v[4:5], s[4:5], v6, s4, v[4:5]
	v_mov_b32_e32 v2, s16
	v_mov_b32_e32 v3, s17
	v_mov_b32_e32 v97, v116
	v_mul_u32_u24_e32 v9, 0x210, v167
	v_readlane_b32 s78, v251, 46
	v_readlane_b32 s79, v251, 47
	v_readlane_b32 s80, v251, 48
	v_readlane_b32 s81, v251, 49
	v_readlane_b32 s86, v251, 54
	v_readlane_b32 s87, v251, 55
	s_add_u32 s30, s82, 0xdc00
	s_mov_b64 s[4:5], 0x5801600
	s_mov_b32 s6, 0xb0000
	v_lshl_add_u64 v[118:119], v[96:97], 0, -2
	v_add_u32_e32 v97, -2, v96
	v_or_b32_e32 v120, 0x4000, v96
	v_mov_b32_e32 v121, v116
	s_mov_b32 s46, 0
	v_cmp_ne_u32_e64 s[0:1], 0, v105
	s_mov_b64 s[86:87], s[78:79]
	s_mov_b64 s[88:89], s[80:81]
	s_mov_b64 s[24:25], 0x2c00
	s_addc_u32 s31, s83, 0
	s_mov_b64 s[80:81], s[60:61]
	v_lshl_add_u64 v[98:99], v[4:5], 0, s[4:5]
	v_mad_u64_u32 v[122:123], s[4:5], v6, s6, v[2:3]
	v_mad_u64_u32 v[124:125], s[4:5], v6, s6, v[0:1]
	s_movk_i32 s47, 0x800
	s_mov_b32 s48, 0x10000
	v_add_u32_e32 v136, v8, v9
	s_movk_i32 s49, 0x1600
	s_movk_i32 s50, 0x7fd
	s_movk_i32 s51, 0x5800
	s_movk_i32 s52, 0x2000
	s_movk_i32 s53, 0x5000
	s_mov_b32 s54, 0x8000
	s_movk_i32 s55, 0xf000
	s_mov_b32 s58, 0x13000
	s_mov_b32 s59, 0xb000
	s_mov_b32 s60, 0xd000
	v_readlane_b32 s12, v252, 0
	v_readlane_b32 s13, v252, 1
	v_readlane_b32 s14, v252, 2
	v_readlane_b32 s15, v252, 3
	s_barrier
	v_readlane_b32 s8, v251, 4
	v_readlane_b32 s9, v251, 5
	v_readlane_b32 s10, v251, 6
	v_readlane_b32 s11, v251, 7
	v_readlane_b32 s73, v251, 41
	v_readlane_b32 s76, v251, 44
	v_readlane_b32 s77, v251, 45
	v_readlane_b32 s84, v251, 52
	v_readlane_b32 s85, v251, 53
	s_branch .LBB0_799
